# gemm_in: last partial round of tiles split in two along K between workgroup pairs (f32 partial sums exchanged through idle scratch, write-through stores + counter)
# speedup vs baseline: 1.0103x; 1.0103x over previous
.LBB0_451:
	v_readlane_b32 s8, v254, 60
	v_readlane_b32 s9, v254, 61
	s_mov_b64 s[0:1], s[88:89]
	s_and_b64 vcc, exec, s[8:9]
	s_cbranch_vccnz .LBB0_640
	s_load_dwordx2 s[34:35], s[0:1], 0xd0
	s_load_dwordx2 s[36:37], s[0:1], 0x100
	s_load_dwordx8 s[20:27], s[0:1], 0x110
	s_load_dwordx2 s[38:39], s[0:1], 0x148
	v_readlane_b32 s54, v254, 0
	v_readlane_b32 s98, v254, 1
	s_movk_i32 s99, 0x660
	s_cmpk_eq_u32 s98, 0x100
	s_cselect_b32 s99, 0x6c0, s99
	s_branch .LBB0_455
.LBB0_453:
	s_or_b64 exec, exec, s[10:11]
.Lgi_sk_tile_end:
	s_barrier
.LBB0_454:
	v_readlane_b32 s0, v254, 1
	s_add_i32 s54, s54, s0
	s_cmp_lt_i32 s54, s99
	v_readlane_b32 s1, v254, 2
	s_cbranch_scc0 .LBB0_640
.LBB0_455:
	s_mov_b32 s57, s54
	s_mov_b32 s55, 0
	s_mov_b32 s84, 0
	s_mov_b32 s85, 28
	s_cmpk_lt_i32 s99, 0x6c0
	s_cbranch_scc1 .Lgi_sk_dec
	s_cmpk_lt_i32 s54, 0x600
	s_cbranch_scc1 .Lgi_sk_dec
	s_mov_b32 s85, 12
	s_mov_b32 s55, 1
	s_sub_u32 s48, s54, 0x600
	s_cmpk_lt_i32 s54, 0x660
	s_cbranch_scc1 .Lgi_sk_dec
	s_mov_b32 s55, 2
	s_movk_i32 s84, 0x800
	s_sub_u32 s57, s54, 96
	s_sub_u32 s48, s57, 0x600
.Lgi_sk_dec:
	s_ashr_i32 s0, s57, 31
	s_lshr_b32 s0, s0, 29
	s_add_i32 s0, s57, s0
	s_ashr_i32 s1, s0, 3
	s_and_b32 s0, s0, -8
	s_sub_i32 s0, s57, s0
	s_cmp_lt_i32 s0, 0
	s_movk_i32 s8, 0xcd
	s_cselect_b32 s8, s8, 0xcc
	s_mul_i32 s9, s8, s0
	s_add_i32 s9, s9, s1
	s_mul_hi_i32 s0, s9, 0x2aaaaaab
	s_lshr_b32 s1, s0, 31
	s_ashr_i32 s40, s0, 5
	s_add_i32 s40, s40, s1
	s_lshl_b32 s8, s40, 3
	s_sub_i32 s0, 0x44, s8
	s_min_u32 s10, s0, 8
	s_mul_i32 s41, s40, 0xc0
	s_sub_i32 s11, s9, s41
	v_cvt_f32_ubyte0_e32 v1, s10
	v_cvt_f32_i32_e32 v0, s11
	v_rcp_iflag_f32_e32 v2, v1
	s_ashr_i32 s0, s11, 30
	s_or_b32 s12, s0, 1
	v_mul_f32_e32 v2, v0, v2
	v_trunc_f32_e32 v2, v2
	v_fma_f32 v0, -v2, v1, v0
	v_cvt_i32_f32_e32 v2, v2
	v_cmp_ge_f32_e64 s[0:1], |v0|, v1
	s_and_b64 s[0:1], s[0:1], exec
	s_cselect_b32 s0, s12, 0
	v_readfirstlane_b32 s1, v2
	s_add_i32 s12, s1, s0
	s_mul_i32 s42, s12, s10
	s_sub_i32 s0, s11, s42
	s_sext_i32_i16 s0, s0
	s_add_i32 s8, s8, s0
	s_cmp_gt_i32 s8, 63
	s_cselect_b64 s[0:1], -1, 0
	s_and_b64 s[10:11], s[2:3], s[0:1]
	s_sext_i32_i16 s0, s12
	s_cmp_gt_i32 s0, 11
	s_cselect_b64 s[12:13], -1, 0
	s_and_b64 s[10:11], s[10:11], s[12:13]
	s_and_b64 vcc, exec, s[10:11]
	s_cbranch_vccnz .LBB0_454
	s_lshl_b32 s10, s8, 8
	s_ashr_i32 s11, s10, 31
	s_lshl_b32 s44, s0, 8
	s_lshl_b64 s[0:1], s[10:11], 12
	v_mov_b32_e32 v142, v167
	s_waitcnt lgkmcnt(0)
	s_add_u32 s12, s20, s0
	s_addc_u32 s13, s21, s1
	v_lshlrev_b32_e32 v12, 4, v142
	v_and_b32_e32 v0, 32, v142
	s_ashr_i32 s45, s44, 31
	v_lshrrev_b32_e32 v1, 1, v142
	v_bitop3_b32 v0, v12, v0, 48 bitop3:0x6c
	s_lshl_b64 s[14:15], s[44:45], 12
	v_lshrrev_b32_e32 v4, 2, v142
	v_and_b32_e32 v10, 32, v1
	v_lshrrev_b32_e32 v11, 1, v0
	v_ashrrev_i32_e32 v13, 3, v142
	v_add_u32_e32 v14, 0x2000, v12
	s_add_u32 s0, s34, s14
	v_or_b32_e32 v0, v11, v10
	v_bfi_b32 v2, 15, v4, v13
	v_ashrrev_i32_e32 v15, 7, v14
	s_addc_u32 s1, s35, s15
	v_lshlrev_b32_e32 v128, 1, v0
	v_add_u32_e32 v128, s84, v128
	v_mov_b32_e32 v129, v165
	v_ashrrev_i32_e32 v3, 31, v2
	v_add_u32_e32 v147, s90, v12
	v_bfi_b32 v4, -16, v15, v4
	v_lshl_add_u64 v[0:1], s[0:1], 0, v[128:129]
	v_lshlrev_b64 v[130:131], 12, v[2:3]
	v_readfirstlane_b32 s0, v147
	v_ashrrev_i32_e32 v5, 31, v4
	v_add_u32_e32 v6, s90, v14
	v_lshl_add_u64 v[2:3], v[0:1], 0, v[130:131]
	s_mov_b32 m0, s0
	v_lshlrev_b64 v[132:133], 12, v[4:5]
	v_readfirstlane_b32 s0, v6
	v_lshl_add_u64 v[16:17], s[12:13], 0, v[128:129]
	v_add_u32_e32 v129, 0, v12
	global_load_lds_dwordx4 v[2:3], off
	v_lshl_add_u64 v[4:5], v[0:1], 0, v[132:133]
	s_mov_b32 m0, s0
	v_readfirstlane_b32 s0, v129
	v_add_u32_e32 v149, 0x2000, v129
	v_readlane_b32 s1, v254, 13
	global_load_lds_dwordx4 v[4:5], off
	v_lshl_add_u64 v[6:7], v[16:17], 0, v[130:131]
	s_mov_b32 m0, s0
	v_readfirstlane_b32 s0, v149
	s_mov_b64 s[46:47], 0x80000
	v_add_u32_e32 v150, s1, v12
	global_load_lds_dwordx4 v[6:7], off
	v_lshl_add_u64 v[8:9], v[16:17], 0, v[132:133]
	s_mov_b32 m0, s0
	v_lshl_add_u64 v[18:19], v[0:1], 0, s[46:47]
	v_readfirstlane_b32 s0, v150
	v_add_u32_e32 v14, s1, v14
	global_load_lds_dwordx4 v[8:9], off
	v_lshl_add_u64 v[20:21], v[18:19], 0, v[130:131]
	s_mov_b32 m0, s0
	v_readfirstlane_b32 s0, v14
	v_add_u32_e32 v151, 0x4000, v129
	global_load_lds_dwordx4 v[20:21], off
	v_lshl_add_u64 v[18:19], v[18:19], 0, v[132:133]
	s_mov_b32 m0, s0
	v_lshl_add_u64 v[16:17], v[16:17], 0, s[46:47]
	v_readfirstlane_b32 s0, v151
	v_add_u32_e32 v153, 0x6000, v129
	global_load_lds_dwordx4 v[18:19], off
	v_lshl_add_u64 v[18:19], v[16:17], 0, v[130:131]
	s_mov_b32 m0, s0
	v_readfirstlane_b32 s0, v153
	global_load_lds_dwordx4 v[18:19], off
	v_lshl_add_u64 v[16:17], v[16:17], 0, v[132:133]
	s_mov_b32 m0, s0
	v_ashrrev_i32_e32 v14, 8, v142
	global_load_lds_dwordx4 v[16:17], off
	v_cmp_eq_u32_e32 vcc, 1, v14
	s_and_saveexec_b64 s[0:1], vcc
	s_cbranch_execz .LBB0_458
	s_barrier
.LBB0_458:
	s_or_b64 exec, exec, s[0:1]
	v_readlane_b32 s1, v254, 11
	v_lshl_add_u64 v[2:3], v[2:3], 0, s[96:97]
	v_add_u32_e32 v156, 0x8000, v129
	v_add_u32_e32 v154, s1, v12
	v_add_u32_e32 v155, 0x2000, v154
	v_readfirstlane_b32 s0, v154
	s_mov_b32 m0, s0
	v_readfirstlane_b32 s0, v155
	s_waitcnt vmcnt(4)
	s_barrier
	global_load_lds_dwordx4 v[2:3], off
	v_lshl_add_u64 v[2:3], v[4:5], 0, s[96:97]
	s_mov_b32 m0, s0
	v_readfirstlane_b32 s0, v156
	v_add_u32_e32 v157, 0xa000, v129
	v_readlane_b32 s11, v254, 44
	global_load_lds_dwordx4 v[2:3], off
	v_lshl_add_u64 v[2:3], v[6:7], 0, s[96:97]
	s_mov_b32 m0, s0
	v_readfirstlane_b32 s0, v157
	v_add_u32_e32 v158, s11, v12
	global_load_lds_dwordx4 v[2:3], off
	v_lshl_add_u64 v[2:3], v[8:9], 0, s[96:97]
	s_mov_b32 m0, s0
	v_lshl_add_u64 v[0:1], v[0:1], 0, s[60:61]
	v_readfirstlane_b32 s0, v158
	v_add_u32_e32 v159, 0x2000, v158
	global_load_lds_dwordx4 v[2:3], off
	v_lshl_add_u64 v[2:3], v[0:1], 0, v[130:131]
	s_mov_b32 m0, s0
	v_readfirstlane_b32 s0, v159
	global_load_lds_dwordx4 v[2:3], off
	v_lshl_add_u64 v[0:1], v[0:1], 0, v[132:133]
	s_mov_b32 m0, s0
	v_and_b32_e32 v17, 15, v142
	global_load_lds_dwordx4 v[0:1], off
	v_lshlrev_b32_e32 v1, 2, v142
	v_and_b32_e32 v18, 48, v142
	v_lshlrev_b32_e32 v0, 6, v17
	v_and_b32_e32 v1, 32, v1
	v_bitop3_b32 v0, v0, v1, v18 bitop3:0x36
	v_readlane_b32 s0, v254, 13
	v_lshlrev_b32_e32 v2, 6, v142
	v_bfe_u32 v16, v142, 2, 4
	v_add_u32_e32 v5, s0, v0
	s_movk_i32 s0, 0x3c0
	v_and_b32_e32 v13, -16, v13
	v_and_b32_e32 v15, -16, v15
	v_add_u32_e32 v4, s90, v0
	v_add_u32_e32 v6, s1, v0
	v_add_u32_e32 v7, s11, v0
	v_add_u32_e32 v12, 0, v0
	v_and_or_b32 v0, v2, s0, v18
	v_and_b32_e32 v8, 0x3000, v2
	v_lshlrev_b32_e32 v9, 13, v14
	v_xad_u32 v14, v0, v1, 0
	v_add_u32_e32 v0, v13, v16
	v_add_u32_e32 v2, v15, v16
	v_ashrrev_i32_e32 v1, 31, v0
	s_add_u32 s0, s34, s14
	v_ashrrev_i32_e32 v3, 31, v2
	v_lshlrev_b64 v[0:1], 12, v[0:1]
	s_addc_u32 s1, s35, s15
	v_lshlrev_b64 v[2:3], 12, v[2:3]
	v_lshl_add_u64 v[134:135], s[0:1], 0, v[0:1]
	v_lshl_add_u64 v[136:137], s[0:1], 0, v[2:3]
	s_sub_i32 s1, s9, s42
	s_sub_i32 s1, s1, s41
	s_sext_i32_i16 s1, s1
	s_lshl_b32 s0, s40, 11
	s_lshl_b32 s1, s1, 8
	s_add_i32 s0, s0, s1
	s_ashr_i32 s1, s0, 31
	s_lshl_b64 s[0:1], s[0:1], 12
	s_add_u32 s0, s20, s0
	s_waitcnt vmcnt(6)
	s_addc_u32 s1, s21, s1
	v_or_b32_e32 v17, 0x800, v9
	v_or_b32_e32 v18, 0x1000, v9
	v_or_b32_e32 v19, 0x1800, v9
	v_lshl_add_u64 v[138:139], s[0:1], 0, v[0:1]
	v_mov_b32_e32 v0, 0
	v_add_lshl_u32 v164, v11, v10, 1
	v_add_u32_e32 v164, s84, v164
	v_lshl_add_u64 v[140:141], s[0:1], 0, v[2:3]
	s_mov_b32 s0, -2
	v_add_u32_e32 v161, v4, v8
	v_add_u32_e32 v146, v12, v9
	v_add_u32_e32 v145, v14, v17
	v_add_u32_e32 v144, v14, v18
	v_add_u32_e32 v143, v14, v19
	v_add_u32_e32 v160, v5, v8
	v_add_u32_e32 v152, v6, v8
	v_add_u32_e32 v148, v7, v8
	v_mov_b32_e32 v1, v0
	v_mov_b32_e32 v2, v0
	v_mov_b32_e32 v3, v0
	v_mov_b32_e32 v4, v0
	v_mov_b32_e32 v5, v0
	v_mov_b32_e32 v6, v0
	v_mov_b32_e32 v7, v0
	v_mov_b32_e32 v8, v0
	v_mov_b32_e32 v9, v0
	v_mov_b32_e32 v10, v0
	v_mov_b32_e32 v11, v0
	v_mov_b32_e32 v12, v0
	v_mov_b32_e32 v13, v0
	v_mov_b32_e32 v14, v0
	v_mov_b32_e32 v15, v0
	v_mov_b32_e32 v16, v0
	v_mov_b32_e32 v17, v0
	v_mov_b32_e32 v18, v0
	v_mov_b32_e32 v19, v0
	v_mov_b32_e32 v20, v0
	v_mov_b32_e32 v21, v0
	v_mov_b32_e32 v22, v0
	v_mov_b32_e32 v23, v0
	v_mov_b32_e32 v24, v0
	v_mov_b32_e32 v25, v0
	v_mov_b32_e32 v26, v0
	v_mov_b32_e32 v27, v0
	v_mov_b32_e32 v28, v0
	v_mov_b32_e32 v29, v0
	v_mov_b32_e32 v30, v0
	v_mov_b32_e32 v31, v0
	v_mov_b32_e32 v32, v0
	v_mov_b32_e32 v33, v0
	v_mov_b32_e32 v34, v0
	v_mov_b32_e32 v35, v0
	v_mov_b32_e32 v36, v0
	v_mov_b32_e32 v37, v0
	v_mov_b32_e32 v38, v0
	v_mov_b32_e32 v39, v0
	v_mov_b32_e32 v40, v0
	v_mov_b32_e32 v41, v0
	v_mov_b32_e32 v42, v0
	v_mov_b32_e32 v43, v0
	v_mov_b32_e32 v44, v0
	v_mov_b32_e32 v45, v0
	v_mov_b32_e32 v46, v0
	v_mov_b32_e32 v47, v0
	v_mov_b32_e32 v48, v0
	v_mov_b32_e32 v49, v0
	v_mov_b32_e32 v50, v0
	v_mov_b32_e32 v51, v0
	v_mov_b32_e32 v52, v0
	v_mov_b32_e32 v53, v0
	v_mov_b32_e32 v54, v0
	v_mov_b32_e32 v55, v0
	v_mov_b32_e32 v56, v0
	v_mov_b32_e32 v57, v0
	v_mov_b32_e32 v58, v0
	v_mov_b32_e32 v59, v0
	v_mov_b32_e32 v60, v0
	v_mov_b32_e32 v61, v0
	v_mov_b32_e32 v62, v0
	v_mov_b32_e32 v63, v0
	v_mov_b32_e32 v64, v0
	v_mov_b32_e32 v65, v0
	v_mov_b32_e32 v66, v0
	v_mov_b32_e32 v67, v0
	v_mov_b32_e32 v68, v0
	v_mov_b32_e32 v69, v0
	v_mov_b32_e32 v70, v0
	v_mov_b32_e32 v71, v0
	v_mov_b32_e32 v72, v0
	v_mov_b32_e32 v73, v0
	v_mov_b32_e32 v74, v0
	v_mov_b32_e32 v75, v0
	v_mov_b32_e32 v76, v0
	v_mov_b32_e32 v77, v0
	v_mov_b32_e32 v78, v0
	v_mov_b32_e32 v79, v0
	v_mov_b32_e32 v80, v0
	v_mov_b32_e32 v81, v0
	v_mov_b32_e32 v82, v0
	v_mov_b32_e32 v83, v0
	v_mov_b32_e32 v84, v0
	v_mov_b32_e32 v85, v0
	v_mov_b32_e32 v86, v0
	v_mov_b32_e32 v87, v0
	v_mov_b32_e32 v88, v0
	v_mov_b32_e32 v89, v0
	v_mov_b32_e32 v90, v0
	v_mov_b32_e32 v91, v0
	v_mov_b32_e32 v92, v0
	v_mov_b32_e32 v93, v0
	v_mov_b32_e32 v94, v0
	v_mov_b32_e32 v95, v0
	v_mov_b32_e32 v96, v0
	v_mov_b32_e32 v97, v0
	v_mov_b32_e32 v98, v0
	v_mov_b32_e32 v99, v0
	v_mov_b32_e32 v100, v0
	v_mov_b32_e32 v101, v0
	v_mov_b32_e32 v102, v0
	v_mov_b32_e32 v103, v0
	v_mov_b32_e32 v104, v0
	v_mov_b32_e32 v105, v0
	v_mov_b32_e32 v106, v0
	v_mov_b32_e32 v107, v0
	v_mov_b32_e32 v108, v0
	v_mov_b32_e32 v109, v0
	v_mov_b32_e32 v110, v0
	v_mov_b32_e32 v111, v0
	v_mov_b32_e32 v112, v0
	v_mov_b32_e32 v113, v0
	v_mov_b32_e32 v114, v0
	v_mov_b32_e32 v115, v0
	v_mov_b32_e32 v116, v0
	v_mov_b32_e32 v117, v0
	v_mov_b32_e32 v118, v0
	v_mov_b32_e32 v119, v0
	v_mov_b32_e32 v120, v0
	v_mov_b32_e32 v121, v0
	v_mov_b32_e32 v122, v0
	v_mov_b32_e32 v123, v0
	v_mov_b32_e32 v124, v0
	v_mov_b32_e32 v125, v0
	v_mov_b32_e32 v126, v0
	v_mov_b32_e32 v127, v0
	s_barrier
.LBB0_459:
	ds_read_b128 v[168:171], v161
	ds_read_b128 v[172:175], v161 offset:1024
	ds_read_b128 v[176:179], v161 offset:2048
	ds_read_b128 v[194:197], v161 offset:3072
	v_add_u32_e32 v162, 0xc000, v129
	v_lshl_add_u64 v[246:247], v[138:139], 0, v[164:165]
	v_readfirstlane_b32 s1, v162
	v_add_u32_e32 v163, 0xe000, v129
	v_lshl_add_u64 v[230:231], v[246:247], 0, s[60:61]
	s_mov_b32 m0, s1
	v_lshl_add_u64 v[248:249], v[140:141], 0, v[164:165]
	v_readfirstlane_b32 s1, v163
	ds_read_b128 v[198:201], v146
	ds_read_b128 v[202:205], v146 offset:1024
	ds_read_b128 v[206:209], v145
	ds_read_b128 v[210:213], v145 offset:1024
	ds_read_b128 v[214:217], v144
	ds_read_b128 v[218:221], v144 offset:1024
	ds_read_b128 v[222:225], v143
	ds_read_b128 v[226:229], v143 offset:1024
	global_load_lds_dwordx4 v[230:231], off
	v_lshl_add_u64 v[230:231], v[248:249], 0, s[60:61]
	s_mov_b32 m0, s1
	s_nop 0
	global_load_lds_dwordx4 v[230:231], off
	s_waitcnt lgkmcnt(8)
	s_barrier
	s_waitcnt lgkmcnt(0)
	s_setprio 1
	s_waitcnt lgkmcnt(0)
	v_mfma_f32_16x16x32_bf16 v[124:127], v[198:201], v[168:171], v[124:127]
	v_mfma_f32_16x16x32_bf16 v[120:123], v[198:201], v[176:179], v[120:123]
	v_mfma_f32_16x16x32_bf16 v[116:119], v[206:209], v[168:171], v[116:119]
	v_mfma_f32_16x16x32_bf16 v[112:115], v[206:209], v[176:179], v[112:115]
	v_mfma_f32_16x16x32_bf16 v[108:111], v[214:217], v[168:171], v[108:111]
	v_mfma_f32_16x16x32_bf16 v[104:107], v[214:217], v[176:179], v[104:107]
	v_mfma_f32_16x16x32_bf16 v[100:103], v[222:225], v[168:171], v[100:103]
	v_mfma_f32_16x16x32_bf16 v[96:99], v[222:225], v[176:179], v[96:99]
	v_mfma_f32_16x16x32_bf16 v[124:127], v[202:205], v[172:175], v[124:127]
	v_mfma_f32_16x16x32_bf16 v[120:123], v[202:205], v[194:197], v[120:123]
	v_mfma_f32_16x16x32_bf16 v[116:119], v[210:213], v[172:175], v[116:119]
	v_mfma_f32_16x16x32_bf16 v[112:115], v[210:213], v[194:197], v[112:115]
	v_mfma_f32_16x16x32_bf16 v[108:111], v[218:221], v[172:175], v[108:111]
	v_mfma_f32_16x16x32_bf16 v[104:107], v[218:221], v[194:197], v[104:107]
	v_mfma_f32_16x16x32_bf16 v[100:103], v[226:229], v[172:175], v[100:103]
	v_mfma_f32_16x16x32_bf16 v[96:99], v[226:229], v[194:197], v[96:99]
	s_setprio 0
	s_barrier
	v_lshl_add_u64 v[250:251], v[134:135], 0, v[164:165]
	v_readfirstlane_b32 s1, v147
	v_lshl_add_u64 v[252:253], v[250:251], 0, s[62:63]
	s_mov_b32 m0, s1
	v_add_u32_e32 v180, 0x2000, v147
	ds_read_b128 v[230:233], v160
	ds_read_b128 v[234:237], v160 offset:1024
	ds_read_b128 v[238:241], v160 offset:2048
	ds_read_b128 v[242:245], v160 offset:3072
	global_load_lds_dwordx4 v[252:253], off
	v_lshl_add_u64 v[252:253], v[136:137], 0, v[164:165]
	v_readfirstlane_b32 s1, v180
	v_lshl_add_u64 v[182:183], v[252:253], 0, s[62:63]
	s_mov_b32 m0, s1
	s_nop 0
	global_load_lds_dwordx4 v[182:183], off
	s_barrier
	s_waitcnt lgkmcnt(0)
	s_setprio 1
	s_waitcnt lgkmcnt(0)
	v_mfma_f32_16x16x32_bf16 v[92:95], v[198:201], v[230:233], v[92:95]
	v_mfma_f32_16x16x32_bf16 v[88:91], v[198:201], v[238:241], v[88:91]
	v_mfma_f32_16x16x32_bf16 v[84:87], v[206:209], v[230:233], v[84:87]
	v_mfma_f32_16x16x32_bf16 v[80:83], v[206:209], v[238:241], v[80:83]
	v_mfma_f32_16x16x32_bf16 v[76:79], v[214:217], v[230:233], v[76:79]
	v_mfma_f32_16x16x32_bf16 v[72:75], v[214:217], v[238:241], v[72:75]
	v_mfma_f32_16x16x32_bf16 v[68:71], v[222:225], v[230:233], v[68:71]
	v_mfma_f32_16x16x32_bf16 v[64:67], v[222:225], v[238:241], v[64:67]
	v_mfma_f32_16x16x32_bf16 v[92:95], v[202:205], v[234:237], v[92:95]
	v_mfma_f32_16x16x32_bf16 v[88:91], v[202:205], v[242:245], v[88:91]
	v_mfma_f32_16x16x32_bf16 v[84:87], v[210:213], v[234:237], v[84:87]
	v_mfma_f32_16x16x32_bf16 v[80:83], v[210:213], v[242:245], v[80:83]
	v_mfma_f32_16x16x32_bf16 v[76:79], v[218:221], v[234:237], v[76:79]
	v_mfma_f32_16x16x32_bf16 v[72:75], v[218:221], v[242:245], v[72:75]
	v_mfma_f32_16x16x32_bf16 v[68:71], v[226:229], v[234:237], v[68:71]
	v_mfma_f32_16x16x32_bf16 v[64:67], v[226:229], v[242:245], v[64:67]
	s_setprio 0
	v_readfirstlane_b32 s1, v129
	v_lshl_add_u64 v[182:183], v[246:247], 0, s[62:63]
	s_mov_b32 m0, s1
	v_readfirstlane_b32 s1, v149
	s_barrier
	ds_read_b128 v[198:201], v146 offset:16384
	ds_read_b128 v[202:205], v146 offset:17408
	ds_read_b128 v[206:209], v145 offset:16384
	ds_read_b128 v[210:213], v145 offset:17408
	ds_read_b128 v[214:217], v144 offset:16384
	ds_read_b128 v[218:221], v144 offset:17408
	ds_read_b128 v[222:225], v143 offset:16384
	ds_read_b128 v[226:229], v143 offset:17408
	global_load_lds_dwordx4 v[182:183], off
	v_lshl_add_u64 v[182:183], v[248:249], 0, s[62:63]
	s_mov_b32 m0, s1
	s_nop 0
	global_load_lds_dwordx4 v[182:183], off
	s_barrier
	s_waitcnt lgkmcnt(0)
	s_setprio 1
	s_waitcnt lgkmcnt(0)
	v_mfma_f32_16x16x32_bf16 v[60:63], v[198:201], v[168:171], v[60:63]
	v_mfma_f32_16x16x32_bf16 v[56:59], v[198:201], v[176:179], v[56:59]
	v_mfma_f32_16x16x32_bf16 v[52:55], v[206:209], v[168:171], v[52:55]
	v_mfma_f32_16x16x32_bf16 v[48:51], v[206:209], v[176:179], v[48:51]
	v_mfma_f32_16x16x32_bf16 v[44:47], v[214:217], v[168:171], v[44:47]
	v_mfma_f32_16x16x32_bf16 v[40:43], v[214:217], v[176:179], v[40:43]
	v_mfma_f32_16x16x32_bf16 v[36:39], v[222:225], v[168:171], v[36:39]
	v_mfma_f32_16x16x32_bf16 v[32:35], v[222:225], v[176:179], v[32:35]
	v_mfma_f32_16x16x32_bf16 v[60:63], v[202:205], v[172:175], v[60:63]
	v_mfma_f32_16x16x32_bf16 v[56:59], v[202:205], v[194:197], v[56:59]
	v_mfma_f32_16x16x32_bf16 v[52:55], v[210:213], v[172:175], v[52:55]
	v_mfma_f32_16x16x32_bf16 v[48:51], v[210:213], v[194:197], v[48:51]
	v_mfma_f32_16x16x32_bf16 v[44:47], v[218:221], v[172:175], v[44:47]
	v_mfma_f32_16x16x32_bf16 v[40:43], v[218:221], v[194:197], v[40:43]
	v_mfma_f32_16x16x32_bf16 v[36:39], v[226:229], v[172:175], v[36:39]
	v_mfma_f32_16x16x32_bf16 v[32:35], v[226:229], v[194:197], v[32:35]
	s_setprio 0
	s_barrier
	v_readfirstlane_b32 s1, v150
	v_add_u32_e32 v170, 0x2000, v150
	v_lshl_add_u64 v[168:169], v[250:251], 0, s[64:65]
	s_mov_b32 m0, s1
	v_readfirstlane_b32 s1, v170
	global_load_lds_dwordx4 v[168:169], off
	v_lshl_add_u64 v[168:169], v[252:253], 0, s[64:65]
	s_mov_b32 m0, s1
	s_nop 0
	global_load_lds_dwordx4 v[168:169], off
	s_waitcnt vmcnt(6)
	s_barrier
	s_setprio 1
	v_mfma_f32_16x16x32_bf16 v[28:31], v[198:201], v[230:233], v[28:31]
	v_mfma_f32_16x16x32_bf16 v[24:27], v[198:201], v[238:241], v[24:27]
	v_mfma_f32_16x16x32_bf16 v[20:23], v[206:209], v[230:233], v[20:23]
	v_mfma_f32_16x16x32_bf16 v[16:19], v[206:209], v[238:241], v[16:19]
	v_mfma_f32_16x16x32_bf16 v[12:15], v[214:217], v[230:233], v[12:15]
	v_mfma_f32_16x16x32_bf16 v[8:11], v[214:217], v[238:241], v[8:11]
	v_mfma_f32_16x16x32_bf16 v[4:7], v[222:225], v[230:233], v[4:7]
	v_mfma_f32_16x16x32_bf16 v[0:3], v[222:225], v[238:241], v[0:3]
	v_mfma_f32_16x16x32_bf16 v[28:31], v[202:205], v[234:237], v[28:31]
	v_mfma_f32_16x16x32_bf16 v[24:27], v[202:205], v[242:245], v[24:27]
	v_mfma_f32_16x16x32_bf16 v[20:23], v[210:213], v[234:237], v[20:23]
	v_mfma_f32_16x16x32_bf16 v[16:19], v[210:213], v[242:245], v[16:19]
	v_mfma_f32_16x16x32_bf16 v[12:15], v[218:221], v[234:237], v[12:15]
	v_mfma_f32_16x16x32_bf16 v[8:11], v[218:221], v[242:245], v[8:11]
	v_mfma_f32_16x16x32_bf16 v[4:7], v[226:229], v[234:237], v[4:7]
	v_mfma_f32_16x16x32_bf16 v[0:3], v[226:229], v[242:245], v[0:3]
	s_setprio 0
	s_barrier
	ds_read_b128 v[168:171], v152
	ds_read_b128 v[172:175], v152 offset:1024
	ds_read_b128 v[176:179], v152 offset:2048
	ds_read_b128 v[194:197], v152 offset:3072
	v_readfirstlane_b32 s1, v151
	v_lshl_add_u64 v[182:183], v[246:247], 0, s[64:65]
	s_mov_b32 m0, s1
	v_readfirstlane_b32 s1, v153
	ds_read_b128 v[198:201], v146 offset:32768
	ds_read_b128 v[202:205], v146 offset:33792
	ds_read_b128 v[206:209], v145 offset:32768
	ds_read_b128 v[210:213], v145 offset:33792
	ds_read_b128 v[214:217], v144 offset:32768
	ds_read_b128 v[218:221], v144 offset:33792
	ds_read_b128 v[222:225], v143 offset:32768
	ds_read_b128 v[226:229], v143 offset:33792
	global_load_lds_dwordx4 v[182:183], off
	v_lshl_add_u64 v[182:183], v[248:249], 0, s[64:65]
	s_mov_b32 m0, s1
	s_nop 0
	global_load_lds_dwordx4 v[182:183], off
	s_waitcnt lgkmcnt(8)
	s_barrier
	s_waitcnt lgkmcnt(0)
	s_setprio 1
	s_waitcnt lgkmcnt(0)
	v_mfma_f32_16x16x32_bf16 v[124:127], v[198:201], v[168:171], v[124:127]
	v_mfma_f32_16x16x32_bf16 v[120:123], v[198:201], v[176:179], v[120:123]
	v_mfma_f32_16x16x32_bf16 v[116:119], v[206:209], v[168:171], v[116:119]
	v_mfma_f32_16x16x32_bf16 v[112:115], v[206:209], v[176:179], v[112:115]
	v_mfma_f32_16x16x32_bf16 v[108:111], v[214:217], v[168:171], v[108:111]
	v_mfma_f32_16x16x32_bf16 v[104:107], v[214:217], v[176:179], v[104:107]
	v_mfma_f32_16x16x32_bf16 v[100:103], v[222:225], v[168:171], v[100:103]
	v_mfma_f32_16x16x32_bf16 v[96:99], v[222:225], v[176:179], v[96:99]
	v_mfma_f32_16x16x32_bf16 v[124:127], v[202:205], v[172:175], v[124:127]
	v_mfma_f32_16x16x32_bf16 v[120:123], v[202:205], v[194:197], v[120:123]
	v_mfma_f32_16x16x32_bf16 v[116:119], v[210:213], v[172:175], v[116:119]
	v_mfma_f32_16x16x32_bf16 v[112:115], v[210:213], v[194:197], v[112:115]
	v_mfma_f32_16x16x32_bf16 v[108:111], v[218:221], v[172:175], v[108:111]
	v_mfma_f32_16x16x32_bf16 v[104:107], v[218:221], v[194:197], v[104:107]
	v_mfma_f32_16x16x32_bf16 v[100:103], v[226:229], v[172:175], v[100:103]
	v_mfma_f32_16x16x32_bf16 v[96:99], v[226:229], v[194:197], v[96:99]
	s_setprio 0
	s_barrier
	v_readfirstlane_b32 s1, v154
	v_lshl_add_u64 v[182:183], v[250:251], 0, s[6:7]
	s_mov_b32 m0, s1
	v_readfirstlane_b32 s1, v155
	ds_read_b128 v[230:233], v148
	ds_read_b128 v[234:237], v148 offset:1024
	ds_read_b128 v[238:241], v148 offset:2048
	ds_read_b128 v[242:245], v148 offset:3072
	global_load_lds_dwordx4 v[182:183], off
	v_lshl_add_u64 v[182:183], v[252:253], 0, s[6:7]
	s_mov_b32 m0, s1
	s_nop 0
	global_load_lds_dwordx4 v[182:183], off
	s_barrier
	s_waitcnt lgkmcnt(0)
	s_setprio 1
	s_waitcnt lgkmcnt(0)
	v_mfma_f32_16x16x32_bf16 v[92:95], v[198:201], v[230:233], v[92:95]
	v_mfma_f32_16x16x32_bf16 v[88:91], v[198:201], v[238:241], v[88:91]
	v_mfma_f32_16x16x32_bf16 v[84:87], v[206:209], v[230:233], v[84:87]
	v_mfma_f32_16x16x32_bf16 v[80:83], v[206:209], v[238:241], v[80:83]
	v_mfma_f32_16x16x32_bf16 v[76:79], v[214:217], v[230:233], v[76:79]
	v_mfma_f32_16x16x32_bf16 v[72:75], v[214:217], v[238:241], v[72:75]
	v_mfma_f32_16x16x32_bf16 v[68:71], v[222:225], v[230:233], v[68:71]
	v_mfma_f32_16x16x32_bf16 v[64:67], v[222:225], v[238:241], v[64:67]
	v_mfma_f32_16x16x32_bf16 v[92:95], v[202:205], v[234:237], v[92:95]
	v_mfma_f32_16x16x32_bf16 v[88:91], v[202:205], v[242:245], v[88:91]
	v_mfma_f32_16x16x32_bf16 v[84:87], v[210:213], v[234:237], v[84:87]
	v_mfma_f32_16x16x32_bf16 v[80:83], v[210:213], v[242:245], v[80:83]
	v_mfma_f32_16x16x32_bf16 v[76:79], v[218:221], v[234:237], v[76:79]
	v_mfma_f32_16x16x32_bf16 v[72:75], v[218:221], v[242:245], v[72:75]
	v_mfma_f32_16x16x32_bf16 v[68:71], v[226:229], v[234:237], v[68:71]
	v_mfma_f32_16x16x32_bf16 v[64:67], v[226:229], v[242:245], v[64:67]
	s_setprio 0
	v_readfirstlane_b32 s1, v156
	v_lshl_add_u64 v[182:183], v[246:247], 0, s[6:7]
	s_mov_b32 m0, s1
	v_readfirstlane_b32 s1, v157
	s_barrier
	ds_read_b128 v[198:201], v146 offset:49152
	ds_read_b128 v[202:205], v146 offset:50176
	ds_read_b128 v[206:209], v145 offset:49152
	ds_read_b128 v[210:213], v145 offset:50176
	ds_read_b128 v[214:217], v144 offset:49152
	ds_read_b128 v[218:221], v144 offset:50176
	ds_read_b128 v[222:225], v143 offset:49152
	ds_read_b128 v[226:229], v143 offset:50176
	global_load_lds_dwordx4 v[182:183], off
	v_lshl_add_u64 v[182:183], v[248:249], 0, s[6:7]
	s_mov_b32 m0, s1
	s_nop 0
	global_load_lds_dwordx4 v[182:183], off
	s_barrier
	s_waitcnt lgkmcnt(0)
	s_setprio 1
	s_waitcnt lgkmcnt(0)
	v_mfma_f32_16x16x32_bf16 v[60:63], v[198:201], v[168:171], v[60:63]
	v_mfma_f32_16x16x32_bf16 v[56:59], v[198:201], v[176:179], v[56:59]
	v_mfma_f32_16x16x32_bf16 v[52:55], v[206:209], v[168:171], v[52:55]
	v_mfma_f32_16x16x32_bf16 v[48:51], v[206:209], v[176:179], v[48:51]
	v_mfma_f32_16x16x32_bf16 v[44:47], v[214:217], v[168:171], v[44:47]
	v_mfma_f32_16x16x32_bf16 v[40:43], v[214:217], v[176:179], v[40:43]
	v_mfma_f32_16x16x32_bf16 v[36:39], v[222:225], v[168:171], v[36:39]
	v_mfma_f32_16x16x32_bf16 v[32:35], v[222:225], v[176:179], v[32:35]
	v_mfma_f32_16x16x32_bf16 v[60:63], v[202:205], v[172:175], v[60:63]
	v_mfma_f32_16x16x32_bf16 v[56:59], v[202:205], v[194:197], v[56:59]
	v_mfma_f32_16x16x32_bf16 v[52:55], v[210:213], v[172:175], v[52:55]
	v_mfma_f32_16x16x32_bf16 v[48:51], v[210:213], v[194:197], v[48:51]
	v_mfma_f32_16x16x32_bf16 v[44:47], v[218:221], v[172:175], v[44:47]
	v_mfma_f32_16x16x32_bf16 v[40:43], v[218:221], v[194:197], v[40:43]
	v_mfma_f32_16x16x32_bf16 v[36:39], v[226:229], v[172:175], v[36:39]
	v_mfma_f32_16x16x32_bf16 v[32:35], v[226:229], v[194:197], v[32:35]
	s_setprio 0
	s_barrier
	v_readfirstlane_b32 s1, v158
	v_lshl_add_u64 v[168:169], v[250:251], 0, s[92:93]
	s_mov_b32 m0, s1
	v_readfirstlane_b32 s1, v159
	global_load_lds_dwordx4 v[168:169], off
	v_lshl_add_u64 v[168:169], v[252:253], 0, s[92:93]
	s_mov_b32 m0, s1
	s_nop 0
	global_load_lds_dwordx4 v[168:169], off
	s_waitcnt vmcnt(6)
	s_barrier
	s_setprio 1
	v_mfma_f32_16x16x32_bf16 v[28:31], v[198:201], v[230:233], v[28:31]
	v_mfma_f32_16x16x32_bf16 v[24:27], v[198:201], v[238:241], v[24:27]
	v_mfma_f32_16x16x32_bf16 v[20:23], v[206:209], v[230:233], v[20:23]
	v_mfma_f32_16x16x32_bf16 v[16:19], v[206:209], v[238:241], v[16:19]
	v_mfma_f32_16x16x32_bf16 v[12:15], v[214:217], v[230:233], v[12:15]
	v_mfma_f32_16x16x32_bf16 v[8:11], v[214:217], v[238:241], v[8:11]
	v_mfma_f32_16x16x32_bf16 v[4:7], v[222:225], v[230:233], v[4:7]
	v_mfma_f32_16x16x32_bf16 v[0:3], v[222:225], v[238:241], v[0:3]
	v_mfma_f32_16x16x32_bf16 v[28:31], v[202:205], v[234:237], v[28:31]
	v_mfma_f32_16x16x32_bf16 v[24:27], v[202:205], v[242:245], v[24:27]
	v_mfma_f32_16x16x32_bf16 v[20:23], v[210:213], v[234:237], v[20:23]
	v_mfma_f32_16x16x32_bf16 v[16:19], v[210:213], v[242:245], v[16:19]
	v_mfma_f32_16x16x32_bf16 v[12:15], v[218:221], v[234:237], v[12:15]
	v_mfma_f32_16x16x32_bf16 v[8:11], v[218:221], v[242:245], v[8:11]
	v_mfma_f32_16x16x32_bf16 v[4:7], v[226:229], v[234:237], v[4:7]
	v_mfma_f32_16x16x32_bf16 v[0:3], v[226:229], v[242:245], v[0:3]
	s_setprio 0
	s_add_i32 s0, s0, 2
	v_lshl_add_u64 v[134:135], v[134:135], 0, s[62:63]
	v_lshl_add_u64 v[136:137], v[136:137], 0, s[62:63]
	v_lshl_add_u64 v[138:139], v[138:139], 0, s[62:63]
	s_cmp_lt_u32 s0, s85
	v_lshl_add_u64 v[140:141], v[140:141], 0, s[62:63]
	s_barrier
	s_cbranch_scc1 .LBB0_459
	v_mov_b32_e32 v129, v165
	v_lshl_add_u64 v[128:129], s[12:13], 0, v[128:129]
	s_add_u32 s0, s85, 3
	s_lshl_b32 s0, s0, 7
	s_add_u32 s0, s0, 0x80000
	s_mov_b32 s1, 0
	v_lshl_add_u64 v[128:129], v[128:129], 0, s[0:1]
	v_readfirstlane_b32 s0, v162
	v_lshl_add_u64 v[130:131], v[128:129], 0, v[130:131]
	s_mov_b32 m0, s0
	v_readfirstlane_b32 s0, v163
	ds_read_b128 v[134:137], v161
	ds_read_b128 v[138:141], v161 offset:1024
	ds_read_b128 v[154:157], v161 offset:2048
	ds_read_b128 v[168:171], v161 offset:3072
	ds_read_b128 v[172:175], v146
	ds_read_b128 v[176:179], v146 offset:1024
	ds_read_b128 v[194:197], v145
	ds_read_b128 v[198:201], v145 offset:1024
	ds_read_b128 v[202:205], v144
	ds_read_b128 v[206:209], v144 offset:1024
	ds_read_b128 v[210:213], v143
	ds_read_b128 v[214:217], v143 offset:1024
	global_load_lds_dwordx4 v[130:131], off
	v_lshl_add_u64 v[128:129], v[128:129], 0, v[132:133]
	s_mov_b32 m0, s0
	s_nop 0
	global_load_lds_dwordx4 v[128:129], off
	s_barrier
	s_waitcnt lgkmcnt(0)
	s_setprio 1
	s_waitcnt lgkmcnt(0)
	v_mfma_f32_16x16x32_bf16 v[124:127], v[172:175], v[134:137], v[124:127]
	v_mfma_f32_16x16x32_bf16 v[120:123], v[172:175], v[154:157], v[120:123]
	v_mfma_f32_16x16x32_bf16 v[116:119], v[194:197], v[134:137], v[116:119]
	v_mfma_f32_16x16x32_bf16 v[112:115], v[194:197], v[154:157], v[112:115]
	v_mfma_f32_16x16x32_bf16 v[108:111], v[202:205], v[134:137], v[108:111]
	v_mfma_f32_16x16x32_bf16 v[104:107], v[202:205], v[154:157], v[104:107]
	v_mfma_f32_16x16x32_bf16 v[100:103], v[210:213], v[134:137], v[100:103]
	v_mfma_f32_16x16x32_bf16 v[96:99], v[210:213], v[154:157], v[96:99]
	v_mfma_f32_16x16x32_bf16 v[124:127], v[176:179], v[138:141], v[124:127]
	v_mfma_f32_16x16x32_bf16 v[120:123], v[176:179], v[168:171], v[120:123]
	v_mfma_f32_16x16x32_bf16 v[116:119], v[198:201], v[138:141], v[116:119]
	v_mfma_f32_16x16x32_bf16 v[112:115], v[198:201], v[168:171], v[112:115]
	v_mfma_f32_16x16x32_bf16 v[108:111], v[206:209], v[138:141], v[108:111]
	v_mfma_f32_16x16x32_bf16 v[104:107], v[206:209], v[168:171], v[104:107]
	v_mfma_f32_16x16x32_bf16 v[100:103], v[214:217], v[138:141], v[100:103]
	v_mfma_f32_16x16x32_bf16 v[96:99], v[214:217], v[168:171], v[96:99]
	s_setprio 0
	s_barrier
	ds_read_b128 v[128:131], v160
	ds_read_b128 v[218:221], v160 offset:1024
	ds_read_b128 v[222:225], v160 offset:2048
	ds_read_b128 v[158:161], v160 offset:3072
	s_barrier
	s_waitcnt lgkmcnt(0)
	s_setprio 1
	s_waitcnt lgkmcnt(0)
	v_mfma_f32_16x16x32_bf16 v[92:95], v[172:175], v[128:131], v[92:95]
	v_mfma_f32_16x16x32_bf16 v[88:91], v[172:175], v[222:225], v[88:91]
	v_mfma_f32_16x16x32_bf16 v[84:87], v[194:197], v[128:131], v[84:87]
	v_mfma_f32_16x16x32_bf16 v[80:83], v[194:197], v[222:225], v[80:83]
	v_mfma_f32_16x16x32_bf16 v[76:79], v[202:205], v[128:131], v[76:79]
	v_mfma_f32_16x16x32_bf16 v[72:75], v[202:205], v[222:225], v[72:75]
	v_mfma_f32_16x16x32_bf16 v[68:71], v[210:213], v[128:131], v[68:71]
	v_mfma_f32_16x16x32_bf16 v[64:67], v[210:213], v[222:225], v[64:67]
	v_mfma_f32_16x16x32_bf16 v[92:95], v[176:179], v[218:221], v[92:95]
	v_mfma_f32_16x16x32_bf16 v[88:91], v[176:179], v[158:161], v[88:91]
	v_mfma_f32_16x16x32_bf16 v[84:87], v[198:201], v[218:221], v[84:87]
	v_mfma_f32_16x16x32_bf16 v[80:83], v[198:201], v[158:161], v[80:83]
	v_mfma_f32_16x16x32_bf16 v[76:79], v[206:209], v[218:221], v[76:79]
	v_mfma_f32_16x16x32_bf16 v[72:75], v[206:209], v[158:161], v[72:75]
	v_mfma_f32_16x16x32_bf16 v[68:71], v[214:217], v[218:221], v[68:71]
	v_mfma_f32_16x16x32_bf16 v[64:67], v[214:217], v[158:161], v[64:67]
	s_setprio 0
	s_barrier
	ds_read_b128 v[172:175], v146 offset:16384
	ds_read_b128 v[176:179], v146 offset:17408
	ds_read_b128 v[194:197], v145 offset:16384
	ds_read_b128 v[198:201], v145 offset:17408
	ds_read_b128 v[202:205], v144 offset:16384
	ds_read_b128 v[206:209], v144 offset:17408
	ds_read_b128 v[210:213], v143 offset:16384
	ds_read_b128 v[214:217], v143 offset:17408
	s_waitcnt vmcnt(4)
	s_barrier
	s_waitcnt lgkmcnt(0)
	s_setprio 1
	s_waitcnt lgkmcnt(0)
	v_mfma_f32_16x16x32_bf16 v[60:63], v[172:175], v[134:137], v[60:63]
	v_mfma_f32_16x16x32_bf16 v[56:59], v[172:175], v[154:157], v[56:59]
	v_mfma_f32_16x16x32_bf16 v[52:55], v[194:197], v[134:137], v[52:55]
	v_mfma_f32_16x16x32_bf16 v[48:51], v[194:197], v[154:157], v[48:51]
	v_mfma_f32_16x16x32_bf16 v[44:47], v[202:205], v[134:137], v[44:47]
	v_mfma_f32_16x16x32_bf16 v[40:43], v[202:205], v[154:157], v[40:43]
	v_mfma_f32_16x16x32_bf16 v[36:39], v[210:213], v[134:137], v[36:39]
	v_mfma_f32_16x16x32_bf16 v[32:35], v[210:213], v[154:157], v[32:35]
	v_mfma_f32_16x16x32_bf16 v[60:63], v[176:179], v[138:141], v[60:63]
	v_mfma_f32_16x16x32_bf16 v[56:59], v[176:179], v[168:171], v[56:59]
	v_mfma_f32_16x16x32_bf16 v[52:55], v[198:201], v[138:141], v[52:55]
	v_mfma_f32_16x16x32_bf16 v[48:51], v[198:201], v[168:171], v[48:51]
	v_mfma_f32_16x16x32_bf16 v[44:47], v[206:209], v[138:141], v[44:47]
	v_mfma_f32_16x16x32_bf16 v[40:43], v[206:209], v[168:171], v[40:43]
	v_mfma_f32_16x16x32_bf16 v[36:39], v[214:217], v[138:141], v[36:39]
	v_mfma_f32_16x16x32_bf16 v[32:35], v[214:217], v[168:171], v[32:35]
	s_setprio 0
	s_setprio 1
	v_mfma_f32_16x16x32_bf16 v[28:31], v[172:175], v[128:131], v[28:31]
	v_mfma_f32_16x16x32_bf16 v[24:27], v[172:175], v[222:225], v[24:27]
	v_mfma_f32_16x16x32_bf16 v[20:23], v[194:197], v[128:131], v[20:23]
	v_mfma_f32_16x16x32_bf16 v[16:19], v[194:197], v[222:225], v[16:19]
	v_mfma_f32_16x16x32_bf16 v[12:15], v[202:205], v[128:131], v[12:15]
	v_mfma_f32_16x16x32_bf16 v[8:11], v[202:205], v[222:225], v[8:11]
	v_mfma_f32_16x16x32_bf16 v[4:7], v[210:213], v[128:131], v[4:7]
	v_mfma_f32_16x16x32_bf16 v[0:3], v[210:213], v[222:225], v[0:3]
	v_mfma_f32_16x16x32_bf16 v[28:31], v[176:179], v[218:221], v[28:31]
	v_mfma_f32_16x16x32_bf16 v[24:27], v[176:179], v[158:161], v[24:27]
	v_mfma_f32_16x16x32_bf16 v[20:23], v[198:201], v[218:221], v[20:23]
	v_mfma_f32_16x16x32_bf16 v[16:19], v[198:201], v[158:161], v[16:19]
	v_mfma_f32_16x16x32_bf16 v[12:15], v[206:209], v[218:221], v[12:15]
	v_mfma_f32_16x16x32_bf16 v[8:11], v[206:209], v[158:161], v[8:11]
	v_mfma_f32_16x16x32_bf16 v[4:7], v[214:217], v[218:221], v[4:7]
	v_mfma_f32_16x16x32_bf16 v[0:3], v[214:217], v[158:161], v[0:3]
	s_setprio 0
	s_barrier
	ds_read_b128 v[128:131], v152
	ds_read_b128 v[132:135], v152 offset:1024
	ds_read_b128 v[136:139], v152 offset:2048
	ds_read_b128 v[150:153], v152 offset:3072
	ds_read_b128 v[154:157], v146 offset:32768
	ds_read_b128 v[158:161], v146 offset:33792
	ds_read_b128 v[168:171], v145 offset:32768
	ds_read_b128 v[172:175], v145 offset:33792
	ds_read_b128 v[176:179], v144 offset:32768
	ds_read_b128 v[194:197], v144 offset:33792
	ds_read_b128 v[198:201], v143 offset:32768
	ds_read_b128 v[202:205], v143 offset:33792
	s_waitcnt vmcnt(2)
	s_barrier
	s_waitcnt lgkmcnt(0)
	s_setprio 1
	s_waitcnt lgkmcnt(0)
	v_mfma_f32_16x16x32_bf16 v[124:127], v[154:157], v[128:131], v[124:127]
	v_mfma_f32_16x16x32_bf16 v[120:123], v[154:157], v[136:139], v[120:123]
	v_mfma_f32_16x16x32_bf16 v[116:119], v[168:171], v[128:131], v[116:119]
	v_mfma_f32_16x16x32_bf16 v[112:115], v[168:171], v[136:139], v[112:115]
	v_mfma_f32_16x16x32_bf16 v[108:111], v[176:179], v[128:131], v[108:111]
	v_mfma_f32_16x16x32_bf16 v[104:107], v[176:179], v[136:139], v[104:107]
	v_mfma_f32_16x16x32_bf16 v[100:103], v[198:201], v[128:131], v[100:103]
	v_mfma_f32_16x16x32_bf16 v[96:99], v[198:201], v[136:139], v[96:99]
	v_mfma_f32_16x16x32_bf16 v[124:127], v[158:161], v[132:135], v[124:127]
	v_mfma_f32_16x16x32_bf16 v[120:123], v[158:161], v[150:153], v[120:123]
	v_mfma_f32_16x16x32_bf16 v[116:119], v[172:175], v[132:135], v[116:119]
	v_mfma_f32_16x16x32_bf16 v[112:115], v[172:175], v[150:153], v[112:115]
	v_mfma_f32_16x16x32_bf16 v[108:111], v[194:197], v[132:135], v[108:111]
	v_mfma_f32_16x16x32_bf16 v[104:107], v[194:197], v[150:153], v[104:107]
	v_mfma_f32_16x16x32_bf16 v[100:103], v[202:205], v[132:135], v[100:103]
	v_mfma_f32_16x16x32_bf16 v[96:99], v[202:205], v[150:153], v[96:99]
	s_setprio 0
	s_barrier
	ds_read_b128 v[206:209], v148
	ds_read_b128 v[210:213], v148 offset:1024
	ds_read_b128 v[214:217], v148 offset:2048
	ds_read_b128 v[218:221], v148 offset:3072
	s_waitcnt vmcnt(0)
	s_barrier
	s_waitcnt lgkmcnt(0)
	s_setprio 1
	s_waitcnt lgkmcnt(0)
	v_mfma_f32_16x16x32_bf16 v[92:95], v[154:157], v[206:209], v[92:95]
	v_mfma_f32_16x16x32_bf16 v[88:91], v[154:157], v[214:217], v[88:91]
	v_mfma_f32_16x16x32_bf16 v[84:87], v[168:171], v[206:209], v[84:87]
	v_mfma_f32_16x16x32_bf16 v[80:83], v[168:171], v[214:217], v[80:83]
	v_mfma_f32_16x16x32_bf16 v[76:79], v[176:179], v[206:209], v[76:79]
	v_mfma_f32_16x16x32_bf16 v[72:75], v[176:179], v[214:217], v[72:75]
	v_mfma_f32_16x16x32_bf16 v[68:71], v[198:201], v[206:209], v[68:71]
	v_mfma_f32_16x16x32_bf16 v[64:67], v[198:201], v[214:217], v[64:67]
	v_mfma_f32_16x16x32_bf16 v[92:95], v[158:161], v[210:213], v[92:95]
	v_mfma_f32_16x16x32_bf16 v[88:91], v[158:161], v[218:221], v[88:91]
	v_mfma_f32_16x16x32_bf16 v[84:87], v[172:175], v[210:213], v[84:87]
	v_mfma_f32_16x16x32_bf16 v[80:83], v[172:175], v[218:221], v[80:83]
	v_mfma_f32_16x16x32_bf16 v[76:79], v[194:197], v[210:213], v[76:79]
	v_mfma_f32_16x16x32_bf16 v[72:75], v[194:197], v[218:221], v[72:75]
	v_mfma_f32_16x16x32_bf16 v[68:71], v[202:205], v[210:213], v[68:71]
	v_mfma_f32_16x16x32_bf16 v[64:67], v[202:205], v[218:221], v[64:67]
	s_setprio 0
	s_barrier
	ds_read_b128 v[154:157], v146 offset:49152
	ds_read_b128 v[146:149], v146 offset:50176
	ds_read_b128 v[158:161], v145 offset:49152
	ds_read_b128 v[168:171], v145 offset:50176
	ds_read_b128 v[172:175], v144 offset:49152
	ds_read_b128 v[176:179], v144 offset:50176
	ds_read_b128 v[194:197], v143 offset:49152
	ds_read_b128 v[198:201], v143 offset:50176
	s_barrier
	s_waitcnt lgkmcnt(0)
	s_setprio 1
	s_waitcnt lgkmcnt(0)
	v_mfma_f32_16x16x32_bf16 v[60:63], v[154:157], v[128:131], v[60:63]
	v_mfma_f32_16x16x32_bf16 v[56:59], v[154:157], v[136:139], v[56:59]
	v_mfma_f32_16x16x32_bf16 v[52:55], v[158:161], v[128:131], v[52:55]
	v_mfma_f32_16x16x32_bf16 v[48:51], v[158:161], v[136:139], v[48:51]
	v_mfma_f32_16x16x32_bf16 v[44:47], v[172:175], v[128:131], v[44:47]
	v_mfma_f32_16x16x32_bf16 v[40:43], v[172:175], v[136:139], v[40:43]
	v_mfma_f32_16x16x32_bf16 v[36:39], v[194:197], v[128:131], v[36:39]
	v_mfma_f32_16x16x32_bf16 v[32:35], v[194:197], v[136:139], v[32:35]
	v_mfma_f32_16x16x32_bf16 v[60:63], v[146:149], v[132:135], v[60:63]
	v_mfma_f32_16x16x32_bf16 v[56:59], v[146:149], v[150:153], v[56:59]
	v_mfma_f32_16x16x32_bf16 v[52:55], v[168:171], v[132:135], v[52:55]
	v_mfma_f32_16x16x32_bf16 v[48:51], v[168:171], v[150:153], v[48:51]
	v_mfma_f32_16x16x32_bf16 v[44:47], v[176:179], v[132:135], v[44:47]
	v_mfma_f32_16x16x32_bf16 v[40:43], v[176:179], v[150:153], v[40:43]
	v_mfma_f32_16x16x32_bf16 v[36:39], v[198:201], v[132:135], v[36:39]
	v_mfma_f32_16x16x32_bf16 v[32:35], v[198:201], v[150:153], v[32:35]
	s_setprio 0
	s_setprio 1
	v_mfma_f32_16x16x32_bf16 v[28:31], v[154:157], v[206:209], v[28:31]
	v_mfma_f32_16x16x32_bf16 v[24:27], v[154:157], v[214:217], v[24:27]
	v_mfma_f32_16x16x32_bf16 v[20:23], v[158:161], v[206:209], v[20:23]
	v_mfma_f32_16x16x32_bf16 v[16:19], v[158:161], v[214:217], v[16:19]
	v_mfma_f32_16x16x32_bf16 v[12:15], v[172:175], v[206:209], v[12:15]
	v_mfma_f32_16x16x32_bf16 v[8:11], v[172:175], v[214:217], v[8:11]
	v_mfma_f32_16x16x32_bf16 v[4:7], v[194:197], v[206:209], v[4:7]
	v_mfma_f32_16x16x32_bf16 v[0:3], v[194:197], v[214:217], v[0:3]
	v_mfma_f32_16x16x32_bf16 v[28:31], v[146:149], v[210:213], v[28:31]
	v_mfma_f32_16x16x32_bf16 v[24:27], v[146:149], v[218:221], v[24:27]
	v_mfma_f32_16x16x32_bf16 v[20:23], v[168:171], v[210:213], v[20:23]
	v_mfma_f32_16x16x32_bf16 v[16:19], v[168:171], v[218:221], v[16:19]
	v_mfma_f32_16x16x32_bf16 v[12:15], v[176:179], v[210:213], v[12:15]
	v_mfma_f32_16x16x32_bf16 v[8:11], v[176:179], v[218:221], v[8:11]
	v_mfma_f32_16x16x32_bf16 v[4:7], v[198:201], v[210:213], v[4:7]
	v_mfma_f32_16x16x32_bf16 v[0:3], v[198:201], v[218:221], v[0:3]
	s_setprio 0
	s_movk_i32 s0, 0x100
	v_cmp_gt_u32_e32 vcc, s0, v142
	s_barrier
	s_and_saveexec_b64 s[0:1], vcc
	s_cbranch_execz .LBB0_462
	s_barrier
.LBB0_462:
	s_or_b64 exec, exec, s[0:1]
	s_cmp_eq_u32 s55, 0
	s_cbranch_scc1 .Lgi_sk_epi
	s_load_dwordx2 s[94:95], s[88:89], 0x168
	s_load_dwordx2 s[84:85], s[88:89], 0x170
	v_lshrrev_b32_e32 v170, 6, v167
	v_and_b32_e32 v171, 63, v167
	v_lshlrev_b32_e32 v170, 15, v170
	v_lshl_add_u32 v170, v171, 4, v170
	s_lshl_b32 s32, s48, 18
	s_lshl_b32 s57, s48, 2
	v_mov_b32_e32 v171, s57
	v_readfirstlane_b32 s98, v167
	s_waitcnt lgkmcnt(0)
	s_add_u32 s94, s94, s32
	s_addc_u32 s95, s95, 0
	s_cmp_eq_u32 s55, 2
	s_cbranch_scc0 .Lgi_sk_fin
	s_nop 7
	s_nop 7
	global_store_dwordx4 v170, v[0:3], s[94:95] sc0 sc1
	global_store_dwordx4 v170, v[4:7], s[94:95] offset:1024 sc0 sc1
	global_store_dwordx4 v170, v[8:11], s[94:95] offset:2048 sc0 sc1
	global_store_dwordx4 v170, v[12:15], s[94:95] offset:3072 sc0 sc1
	v_add_u32_e32 v170, 0x1000, v170
	global_store_dwordx4 v170, v[16:19], s[94:95] sc0 sc1
	global_store_dwordx4 v170, v[20:23], s[94:95] offset:1024 sc0 sc1
	global_store_dwordx4 v170, v[24:27], s[94:95] offset:2048 sc0 sc1
	global_store_dwordx4 v170, v[28:31], s[94:95] offset:3072 sc0 sc1
	v_add_u32_e32 v170, 0x1000, v170
	global_store_dwordx4 v170, v[32:35], s[94:95] sc0 sc1
	global_store_dwordx4 v170, v[36:39], s[94:95] offset:1024 sc0 sc1
	global_store_dwordx4 v170, v[40:43], s[94:95] offset:2048 sc0 sc1
	global_store_dwordx4 v170, v[44:47], s[94:95] offset:3072 sc0 sc1
	v_add_u32_e32 v170, 0x1000, v170
	global_store_dwordx4 v170, v[48:51], s[94:95] sc0 sc1
	global_store_dwordx4 v170, v[52:55], s[94:95] offset:1024 sc0 sc1
	global_store_dwordx4 v170, v[56:59], s[94:95] offset:2048 sc0 sc1
	global_store_dwordx4 v170, v[60:63], s[94:95] offset:3072 sc0 sc1
	v_add_u32_e32 v170, 0x1000, v170
	global_store_dwordx4 v170, v[64:67], s[94:95] sc0 sc1
	global_store_dwordx4 v170, v[68:71], s[94:95] offset:1024 sc0 sc1
	global_store_dwordx4 v170, v[72:75], s[94:95] offset:2048 sc0 sc1
	global_store_dwordx4 v170, v[76:79], s[94:95] offset:3072 sc0 sc1
	v_add_u32_e32 v170, 0x1000, v170
	global_store_dwordx4 v170, v[80:83], s[94:95] sc0 sc1
	global_store_dwordx4 v170, v[84:87], s[94:95] offset:1024 sc0 sc1
	global_store_dwordx4 v170, v[88:91], s[94:95] offset:2048 sc0 sc1
	global_store_dwordx4 v170, v[92:95], s[94:95] offset:3072 sc0 sc1
	v_add_u32_e32 v170, 0x1000, v170
	global_store_dwordx4 v170, v[96:99], s[94:95] sc0 sc1
	global_store_dwordx4 v170, v[100:103], s[94:95] offset:1024 sc0 sc1
	global_store_dwordx4 v170, v[104:107], s[94:95] offset:2048 sc0 sc1
	global_store_dwordx4 v170, v[108:111], s[94:95] offset:3072 sc0 sc1
	v_add_u32_e32 v170, 0x1000, v170
	global_store_dwordx4 v170, v[112:115], s[94:95] sc0 sc1
	global_store_dwordx4 v170, v[116:119], s[94:95] offset:1024 sc0 sc1
	global_store_dwordx4 v170, v[120:123], s[94:95] offset:2048 sc0 sc1
	global_store_dwordx4 v170, v[124:127], s[94:95] offset:3072 sc0 sc1
	v_add_u32_e32 v170, 0x1000, v170
	s_waitcnt vmcnt(0)
	s_barrier
	s_cmp_lt_u32 s98, 64
	s_cbranch_scc0 .Lgi_sk_tile_end
	s_mov_b64 exec, 1
	v_mov_b32_e32 v172, 1
	global_atomic_add v171, v172, s[84:85]
	s_waitcnt vmcnt(0)
	s_mov_b64 exec, -1
	s_branch .Lgi_sk_tile_end
.Lgi_sk_fin:
	s_cmp_lt_u32 s98, 64
	s_cbranch_scc0 .Lgi_sk_wd
	v_readlane_b32 s57, v255, 0
	s_add_u32 s57, s57, 1
	s_mov_b32 s32, 0
.Lgi_sk_poll:
	global_load_dword v172, v171, s[84:85] sc1
	s_waitcnt vmcnt(0)
	v_readfirstlane_b32 s98, v172
	s_cmp_ge_u32 s98, s57
	s_cbranch_scc1 .Lgi_sk_got
	s_sleep 1
	s_add_u32 s32, s32, 1
	s_cmp_lt_u32 s32, 0x200000
	s_cbranch_scc1 .Lgi_sk_poll
.Lgi_sk_got:
	buffer_inv sc1
	s_waitcnt vmcnt(0)
.Lgi_sk_wd:
	s_barrier
	global_load_dwordx4 v[194:197], v170, s[94:95] sc0 sc1
	global_load_dwordx4 v[198:201], v170, s[94:95] offset:1024 sc0 sc1
	global_load_dwordx4 v[202:205], v170, s[94:95] offset:2048 sc0 sc1
	global_load_dwordx4 v[206:209], v170, s[94:95] offset:3072 sc0 sc1
	v_add_u32_e32 v170, 0x1000, v170
	global_load_dwordx4 v[210:213], v170, s[94:95] sc0 sc1
	global_load_dwordx4 v[214:217], v170, s[94:95] offset:1024 sc0 sc1
	global_load_dwordx4 v[218:221], v170, s[94:95] offset:2048 sc0 sc1
	global_load_dwordx4 v[222:225], v170, s[94:95] offset:3072 sc0 sc1
	v_add_u32_e32 v170, 0x1000, v170
	global_load_dwordx4 v[226:229], v170, s[94:95] sc0 sc1
	global_load_dwordx4 v[230:233], v170, s[94:95] offset:1024 sc0 sc1
	global_load_dwordx4 v[234:237], v170, s[94:95] offset:2048 sc0 sc1
	global_load_dwordx4 v[238:241], v170, s[94:95] offset:3072 sc0 sc1
	v_add_u32_e32 v170, 0x1000, v170
	global_load_dwordx4 v[242:245], v170, s[94:95] sc0 sc1
	global_load_dwordx4 v[246:249], v170, s[94:95] offset:1024 sc0 sc1
	global_load_dwordx4 v[250:253], v170, s[94:95] offset:2048 sc0 sc1
	s_waitcnt vmcnt(7)
	v_pk_add_f32 v[0:1], v[0:1], v[194:195]
	v_pk_add_f32 v[2:3], v[2:3], v[196:197]
	v_pk_add_f32 v[4:5], v[4:5], v[198:199]
	v_pk_add_f32 v[6:7], v[6:7], v[200:201]
	v_pk_add_f32 v[8:9], v[8:9], v[202:203]
	v_pk_add_f32 v[10:11], v[10:11], v[204:205]
	v_pk_add_f32 v[12:13], v[12:13], v[206:207]
	v_pk_add_f32 v[14:15], v[14:15], v[208:209]
	v_pk_add_f32 v[16:17], v[16:17], v[210:211]
	v_pk_add_f32 v[18:19], v[18:19], v[212:213]
	v_pk_add_f32 v[20:21], v[20:21], v[214:215]
	v_pk_add_f32 v[22:23], v[22:23], v[216:217]
	v_pk_add_f32 v[24:25], v[24:25], v[218:219]
	v_pk_add_f32 v[26:27], v[26:27], v[220:221]
	v_pk_add_f32 v[28:29], v[28:29], v[222:223]
	v_pk_add_f32 v[30:31], v[30:31], v[224:225]
	global_load_dwordx4 v[194:197], v170, s[94:95] offset:3072 sc0 sc1
	v_add_u32_e32 v170, 0x1000, v170
	global_load_dwordx4 v[198:201], v170, s[94:95] sc0 sc1
	global_load_dwordx4 v[202:205], v170, s[94:95] offset:1024 sc0 sc1
	global_load_dwordx4 v[206:209], v170, s[94:95] offset:2048 sc0 sc1
	global_load_dwordx4 v[210:213], v170, s[94:95] offset:3072 sc0 sc1
	v_add_u32_e32 v170, 0x1000, v170
	global_load_dwordx4 v[214:217], v170, s[94:95] sc0 sc1
	global_load_dwordx4 v[218:221], v170, s[94:95] offset:1024 sc0 sc1
	global_load_dwordx4 v[222:225], v170, s[94:95] offset:2048 sc0 sc1
	s_waitcnt vmcnt(8)
	v_pk_add_f32 v[32:33], v[32:33], v[226:227]
	v_pk_add_f32 v[34:35], v[34:35], v[228:229]
	v_pk_add_f32 v[36:37], v[36:37], v[230:231]
	v_pk_add_f32 v[38:39], v[38:39], v[232:233]
	v_pk_add_f32 v[40:41], v[40:41], v[234:235]
	v_pk_add_f32 v[42:43], v[42:43], v[236:237]
	v_pk_add_f32 v[44:45], v[44:45], v[238:239]
	v_pk_add_f32 v[46:47], v[46:47], v[240:241]
	v_pk_add_f32 v[48:49], v[48:49], v[242:243]
	v_pk_add_f32 v[50:51], v[50:51], v[244:245]
	v_pk_add_f32 v[52:53], v[52:53], v[246:247]
	v_pk_add_f32 v[54:55], v[54:55], v[248:249]
	v_pk_add_f32 v[56:57], v[56:57], v[250:251]
	v_pk_add_f32 v[58:59], v[58:59], v[252:253]
	global_load_dwordx4 v[226:229], v170, s[94:95] offset:3072 sc0 sc1
	v_add_u32_e32 v170, 0x1000, v170
	global_load_dwordx4 v[230:233], v170, s[94:95] sc0 sc1
	global_load_dwordx4 v[234:237], v170, s[94:95] offset:1024 sc0 sc1
	global_load_dwordx4 v[238:241], v170, s[94:95] offset:2048 sc0 sc1
	global_load_dwordx4 v[242:245], v170, s[94:95] offset:3072 sc0 sc1
	v_add_u32_e32 v170, 0x1000, v170
	global_load_dwordx4 v[246:249], v170, s[94:95] sc0 sc1
	global_load_dwordx4 v[250:253], v170, s[94:95] offset:1024 sc0 sc1
	s_waitcnt vmcnt(7)
	v_pk_add_f32 v[60:61], v[60:61], v[194:195]
	v_pk_add_f32 v[62:63], v[62:63], v[196:197]
	v_pk_add_f32 v[64:65], v[64:65], v[198:199]
	v_pk_add_f32 v[66:67], v[66:67], v[200:201]
	v_pk_add_f32 v[68:69], v[68:69], v[202:203]
	v_pk_add_f32 v[70:71], v[70:71], v[204:205]
	v_pk_add_f32 v[72:73], v[72:73], v[206:207]
	v_pk_add_f32 v[74:75], v[74:75], v[208:209]
	v_pk_add_f32 v[76:77], v[76:77], v[210:211]
	v_pk_add_f32 v[78:79], v[78:79], v[212:213]
	v_pk_add_f32 v[80:81], v[80:81], v[214:215]
	v_pk_add_f32 v[82:83], v[82:83], v[216:217]
	v_pk_add_f32 v[84:85], v[84:85], v[218:219]
	v_pk_add_f32 v[86:87], v[86:87], v[220:221]
	v_pk_add_f32 v[88:89], v[88:89], v[222:223]
	v_pk_add_f32 v[90:91], v[90:91], v[224:225]
	global_load_dwordx4 v[194:197], v170, s[94:95] offset:2048 sc0 sc1
	global_load_dwordx4 v[198:201], v170, s[94:95] offset:3072 sc0 sc1
	v_add_u32_e32 v170, 0x1000, v170
	s_waitcnt vmcnt(2)
	v_pk_add_f32 v[92:93], v[92:93], v[226:227]
	v_pk_add_f32 v[94:95], v[94:95], v[228:229]
	v_pk_add_f32 v[96:97], v[96:97], v[230:231]
	v_pk_add_f32 v[98:99], v[98:99], v[232:233]
	v_pk_add_f32 v[100:101], v[100:101], v[234:235]
	v_pk_add_f32 v[102:103], v[102:103], v[236:237]
	v_pk_add_f32 v[104:105], v[104:105], v[238:239]
	v_pk_add_f32 v[106:107], v[106:107], v[240:241]
	v_pk_add_f32 v[108:109], v[108:109], v[242:243]
	v_pk_add_f32 v[110:111], v[110:111], v[244:245]
	v_pk_add_f32 v[112:113], v[112:113], v[246:247]
	v_pk_add_f32 v[114:115], v[114:115], v[248:249]
	v_pk_add_f32 v[116:117], v[116:117], v[250:251]
	v_pk_add_f32 v[118:119], v[118:119], v[252:253]
	s_waitcnt vmcnt(0)
	v_pk_add_f32 v[120:121], v[120:121], v[194:195]
	v_pk_add_f32 v[122:123], v[122:123], v[196:197]
	v_pk_add_f32 v[124:125], v[124:125], v[198:199]
	v_pk_add_f32 v[126:127], v[126:127], v[200:201]
.Lgi_sk_epi:
	v_mov_b32_e32 v129, v167
	s_cmp_gt_i32 s8, 63
	v_ashrrev_i32_e32 v130, 2, v129
	v_and_b32_e32 v128, 0xffffffc0, v130
	v_and_b32_e32 v164, 15, v129
	s_cselect_b64 s[42:43], -1, 0
	v_add_u32_e32 v158, s10, v128
	v_lshrrev_b32_e32 v128, 1, v129
	v_lshrrev_b32_e32 v129, 2, v129
	s_ashr_i32 s0, s8, 4
	v_and_b32_e32 v128, 0x60, v128
	v_and_b32_e32 v151, 12, v129
	s_mul_hi_i32 s41, s0, 0xc00
	s_mul_i32 s40, s0, 0xc00
	v_add_u32_e32 v129, 0xffffc000, v158
	s_movk_i32 s0, 0xfc0
	v_or_b32_e32 v128, s44, v128
	v_ashrrev_i32_e32 v132, 8, v129
	v_and_or_b32 v129, v158, s0, v151
	s_movk_i32 s0, 0xb7f
	v_and_or_b32 v162, v130, s75, v151
	v_mul_hi_i32_i24_e32 v131, 0xc00, v132
	v_mul_i32_i24_e32 v130, 0xc00, v132
	v_cmp_lt_i32_e64 s[12:13], s0, v128
	s_and_saveexec_b64 s[0:1], s[12:13]
	s_xor_b64 s[10:11], exec, s[0:1]
	s_cbranch_execz .LBB0_470
	s_cmpk_gt_u32 s44, 0x177f
	s_cbranch_scc1 .LBB0_470
	v_add_u32_e32 v133, 0xfffff480, v128
	s_mov_b64 s[0:1], -1
	s_and_b64 vcc, exec, s[42:43]
	s_cbranch_vccz .LBB0_468
	v_readlane_b32 s0, v254, 56
	v_readlane_b32 s1, v254, 57
	s_andn2_b64 vcc, exec, s[0:1]
	s_cbranch_vccnz .LBB0_467
	v_or_b32_e32 v134, v133, v164
	v_mov_b32_e32 v135, v165
	v_lshl_add_u64 v[138:139], v[130:131], 0, v[134:135]
	v_or_b32_e32 v134, 16, v134
	v_lshlrev_b64 v[138:139], 9, v[138:139]
	v_lshl_add_u64 v[134:135], v[130:131], 0, v[134:135]
	v_lshl_add_u64 v[138:139], s[26:27], 0, v[138:139]
	v_lshlrev_b32_e32 v140, 1, v162
	v_mov_b32_e32 v141, v165
	v_lshlrev_b64 v[134:135], 9, v[134:135]
	v_cvt_pk_bf16_f32 v136, v124, v125
	v_cvt_pk_bf16_f32 v137, v126, v127
	v_lshl_add_u64 v[138:139], v[138:139], 0, v[140:141]
	v_lshl_add_u64 v[134:135], s[26:27], 0, v[134:135]
	global_store_dwordx2 v[138:139], v[136:137], off
	v_cvt_pk_bf16_f32 v136, v120, v121
	v_cvt_pk_bf16_f32 v137, v122, v123
	v_lshl_add_u64 v[134:135], v[134:135], 0, v[140:141]
	global_store_dwordx2 v[134:135], v[136:137], off
	v_cvt_pk_bf16_f32 v136, v116, v117
	v_cvt_pk_bf16_f32 v137, v118, v119
	global_store_dwordx2 v[138:139], v[136:137], off offset:32
	v_cvt_pk_bf16_f32 v136, v112, v113
	v_cvt_pk_bf16_f32 v137, v114, v115
	global_store_dwordx2 v[134:135], v[136:137], off offset:32
	v_cvt_pk_bf16_f32 v136, v108, v109
	v_cvt_pk_bf16_f32 v137, v110, v111
	global_store_dwordx2 v[138:139], v[136:137], off offset:64
	v_cvt_pk_bf16_f32 v136, v104, v105
	v_cvt_pk_bf16_f32 v137, v106, v107
	global_store_dwordx2 v[134:135], v[136:137], off offset:64
	v_cvt_pk_bf16_f32 v136, v100, v101
	v_cvt_pk_bf16_f32 v137, v102, v103
	global_store_dwordx2 v[138:139], v[136:137], off offset:96
	v_cvt_pk_bf16_f32 v136, v96, v97
	v_cvt_pk_bf16_f32 v137, v98, v99
	global_store_dwordx2 v[134:135], v[136:137], off offset:96
